# grid barrier: cross-XCD arrival counter removed; every XCD leader adds 1 to each XCD's release word after its write-back and all workgroups wait for (gen+1)*nXCD
# speedup vs baseline: 1.0070x; 1.0014x over previous
; __device__ __forceinline__ unsigned xb_ld(unsigned* p)              { return __hip_atomic_load(p, __ATOMIC_RELAXED, __HIP_MEMORY_SCOPE_AGENT); }
; __device__ __forceinline__ unsigned xb_add(unsigned* p, unsigned v) { return __hip_atomic_fetch_add(p, v, __ATOMIC_RELAXED, __HIP_MEMORY_SCOPE_AGENT); }
; #define XB_SPIN(cond, bar) do { unsigned _sp = 0; while (cond) { __builtin_amdgcn_s_sleep(1); \
;     if ((++_sp & 255u) == 0u) { if (xb_ld(&(bar)[XB_TMO])) break; if (_sp > XB_SPIN_CAP) { atomicAdd(&(bar)[XB_TMO], 1u); break; } } } } while (0)
; __device__ __forceinline__ void xcd_barrier(unsigned* bar, volatile LAS unsigned* st, bool tid0) {
;     ...
;         __builtin_amdgcn_s_waitcnt(0);
;         unsigned nloc = st[0], nx = st[1];
;         if (nloc == 0u) { xcd_barrier_complete(bar, x, nloc, nx); st[0] = nloc; st[1] = nx; }
;         const unsigned old = xb_add(&bar[XB_XSUB(x)], 1u);
;         const unsigned gen = old / nloc;
;         if (old + 1u == (gen + 1u) * nloc) {
;             __builtin_amdgcn_fence(__ATOMIC_RELEASE, "agent");
;             asm volatile("s_waitcnt vmcnt(0)" ::: "memory");
;             const unsigned og = xb_add(&bar[XB_TOP], 1u);
;             const unsigned tg = og / nx;
;             if (og + 1u == (tg + 1u) * nx) xb_add(&bar[XB_TOPGEN], 1u);
;             else XB_SPIN(xb_ld(&bar[XB_TOPGEN]) == tg, bar);
;             __builtin_amdgcn_fence(__ATOMIC_ACQUIRE, "agent");
;             xb_add(&bar[XB_XGEN(x)], 1u);
;             asm volatile("s_waitcnt vmcnt(0)" ::: "memory");
;         } else {
;             XB_SPIN(xb_ld(&bar[XB_XGEN(x)]) == gen, bar);
;             __builtin_amdgcn_fence(__ATOMIC_ACQUIRE, "agent");
;             asm volatile("s_waitcnt vmcnt(0)" ::: "memory");
;         }
.LBB0_47:
	s_or_b64 exec, exec, s[8:9]
	buffer_inv sc1
	v_cvt_f32_u32_e32 v5, v3
	s_waitcnt vmcnt(1)
	v_readfirstlane_b32 s2, v4
	v_sub_u32_e32 v4, 0, v3
	v_rcp_iflag_f32_e32 v5, v5
	v_add_u32_e32 v6, s2, v2
	v_mul_f32_e32 v5, 0x4f7ffffe, v5
	v_cvt_u32_f32_e32 v5, v5
	v_mul_lo_u32 v2, v4, v5
	v_mul_hi_u32 v2, v5, v2
	v_add_u32_e32 v2, v5, v2
	v_mul_hi_u32 v2, v6, v2
	v_mul_lo_u32 v4, v2, v3
	v_sub_u32_e32 v4, v6, v4
	v_add_u32_e32 v5, 1, v2
	v_cmp_ge_u32_e32 vcc, v4, v3
	s_nop 1
	v_cndmask_b32_e32 v2, v2, v5, vcc
	v_sub_u32_e32 v5, v4, v3
	v_cndmask_b32_e32 v4, v4, v5, vcc
	v_add_u32_e32 v5, 1, v2
	v_cmp_ge_u32_e32 vcc, v4, v3
	v_add_u32_e32 v4, 1, v6
	s_nop 0
	v_cndmask_b32_e32 v2, v2, v5, vcc
	v_mul_lo_u32 v5, v3, v2
	v_add_u32_e32 v3, v5, v3
	v_cmp_ne_u32_e32 vcc, v4, v3
	s_waitcnt lgkmcnt(0)
	v_add_u32_e32 v2, 1, v2
	v_mul_lo_u32 v2, v2, v1
	s_cbranch_vccnz .Lxb2_follow_0
	buffer_wbl2 sc1
	s_waitcnt vmcnt(0)
	v_mov_b32_e32 v14, 0x2400
	v_mov_b32_e32 v15, 1
	global_atomic_add v14, v15, s[52:53]
	global_atomic_add v14, v15, s[52:53] offset:256
	global_atomic_add v14, v15, s[52:53] offset:512
	global_atomic_add v14, v15, s[52:53] offset:768
	global_atomic_add v14, v15, s[52:53] offset:1024
	global_atomic_add v14, v15, s[52:53] offset:1280
	global_atomic_add v14, v15, s[52:53] offset:1536
	global_atomic_add v14, v15, s[52:53] offset:1792
	global_atomic_add v14, v15, s[52:53] offset:2048
	global_atomic_add v14, v15, s[52:53] offset:2304
	global_atomic_add v14, v15, s[52:53] offset:2560
	global_atomic_add v14, v15, s[52:53] offset:2816
	global_atomic_add v14, v15, s[52:53] offset:3072
	global_atomic_add v14, v15, s[52:53] offset:3328
	global_atomic_add v14, v15, s[52:53] offset:3584
	global_atomic_add v14, v15, s[52:53] offset:3840
	s_mov_b64 vcc, exec
.Lxb2_follow_0:
	s_and_saveexec_b64 s[2:3], vcc
	s_xor_b64 s[6:7], exec, s[2:3]
	s_cbranch_execz .LBB0_61
	s_waitcnt lgkmcnt(0)
	v_mov_b32_e32 v1, 0x2000
	global_load_dword v1, v1, s[4:5] offset:1024 sc1
	s_add_u32 s10, s4, 0x2400
	s_addc_u32 s11, s5, 0
	s_waitcnt vmcnt(0)
	v_cmp_lt_u32_e32 vcc, v1, v2
	s_and_saveexec_b64 s[8:9], vcc
	s_cbranch_execz .LBB0_60
	s_mov_b32 s2, 1
	s_mov_b64 s[12:13], 0
	v_mov_b32_e32 v1, 0
	s_branch .LBB0_51

; __device__ __forceinline__ unsigned xb_ld(unsigned* p)              { return __hip_atomic_load(p, __ATOMIC_RELAXED, __HIP_MEMORY_SCOPE_AGENT); }
; #define XB_SPIN(cond, bar) do { unsigned _sp = 0; while (cond) { __builtin_amdgcn_s_sleep(1); \
;     if ((++_sp & 255u) == 0u) { if (xb_ld(&(bar)[XB_TMO])) break; if (_sp > XB_SPIN_CAP) { atomicAdd(&(bar)[XB_TMO], 1u); break; } } } } while (0)
; __device__ __forceinline__ void xcd_barrier(unsigned* bar, volatile LAS unsigned* st, bool tid0) {
;     ...
;             XB_SPIN(xb_ld(&bar[XB_XGEN(x)]) == gen, bar);
;             __builtin_amdgcn_fence(__ATOMIC_ACQUIRE, "agent");
;             asm volatile("s_waitcnt vmcnt(0)" ::: "memory");
.LBB0_53:
	global_load_dword v3, v1, s[10:11] sc1
	s_add_i32 s2, s2, 1
	s_mov_b64 s[18:19], -1
	s_waitcnt vmcnt(0)
	v_cmp_ge_u32_e32 vcc, v3, v2
	s_orn2_b64 s[16:17], vcc, exec
	s_branch .LBB0_50

; __device__ __forceinline__ unsigned xb_ld(unsigned* p)              { return __hip_atomic_load(p, __ATOMIC_RELAXED, __HIP_MEMORY_SCOPE_AGENT); }
; __device__ __forceinline__ unsigned xb_add(unsigned* p, unsigned v) { return __hip_atomic_fetch_add(p, v, __ATOMIC_RELAXED, __HIP_MEMORY_SCOPE_AGENT); }
; #define XB_SPIN(cond, bar) do { unsigned _sp = 0; while (cond) { __builtin_amdgcn_s_sleep(1); \
;     if ((++_sp & 255u) == 0u) { if (xb_ld(&(bar)[XB_TMO])) break; if (_sp > XB_SPIN_CAP) { atomicAdd(&(bar)[XB_TMO], 1u); break; } } } } while (0)
; __device__ __forceinline__ void xcd_barrier(unsigned* bar, volatile LAS unsigned* st, bool tid0) {
;     ...
;         __builtin_amdgcn_s_waitcnt(0);
;         unsigned nloc = st[0], nx = st[1];
;         if (nloc == 0u) { xcd_barrier_complete(bar, x, nloc, nx); st[0] = nloc; st[1] = nx; }
;         const unsigned old = xb_add(&bar[XB_XSUB(x)], 1u);
;         const unsigned gen = old / nloc;
;         if (old + 1u == (gen + 1u) * nloc) {
;             __builtin_amdgcn_fence(__ATOMIC_RELEASE, "agent");
;             asm volatile("s_waitcnt vmcnt(0)" ::: "memory");
;             const unsigned og = xb_add(&bar[XB_TOP], 1u);
;             const unsigned tg = og / nx;
;             if (og + 1u == (tg + 1u) * nx) xb_add(&bar[XB_TOPGEN], 1u);
;             else XB_SPIN(xb_ld(&bar[XB_TOPGEN]) == tg, bar);
;             __builtin_amdgcn_fence(__ATOMIC_ACQUIRE, "agent");
;             xb_add(&bar[XB_XGEN(x)], 1u);
;             asm volatile("s_waitcnt vmcnt(0)" ::: "memory");
;         } else {
;             XB_SPIN(xb_ld(&bar[XB_XGEN(x)]) == gen, bar);
;             __builtin_amdgcn_fence(__ATOMIC_ACQUIRE, "agent");
;             asm volatile("s_waitcnt vmcnt(0)" ::: "memory");
;         }
.LBB0_189:
	s_or_b64 exec, exec, s[8:9]
	buffer_inv sc1
	v_cvt_f32_u32_e32 v4, v2
	s_waitcnt vmcnt(1)
	v_readfirstlane_b32 s2, v3
	v_sub_u32_e32 v3, 0, v2
	v_rcp_iflag_f32_e32 v4, v4
	v_add_u32_e32 v5, s2, v1
	v_mul_f32_e32 v4, 0x4f7ffffe, v4
	v_cvt_u32_f32_e32 v4, v4
	v_mul_lo_u32 v1, v3, v4
	v_mul_hi_u32 v1, v4, v1
	v_add_u32_e32 v1, v4, v1
	v_mul_hi_u32 v1, v5, v1
	v_mul_lo_u32 v3, v1, v2
	v_sub_u32_e32 v3, v5, v3
	v_add_u32_e32 v4, 1, v1
	v_cmp_ge_u32_e32 vcc, v3, v2
	s_nop 1
	v_cndmask_b32_e32 v1, v1, v4, vcc
	v_sub_u32_e32 v4, v3, v2
	v_cndmask_b32_e32 v3, v3, v4, vcc
	v_add_u32_e32 v4, 1, v1
	v_cmp_ge_u32_e32 vcc, v3, v2
	v_add_u32_e32 v3, 1, v5
	s_nop 0
	v_cndmask_b32_e32 v1, v1, v4, vcc
	v_mul_lo_u32 v4, v2, v1
	v_add_u32_e32 v2, v4, v2
	v_cmp_ne_u32_e32 vcc, v3, v2
	s_waitcnt lgkmcnt(0)
	v_add_u32_e32 v1, 1, v1
	v_mul_lo_u32 v1, v1, v0
	s_cbranch_vccnz .Lxb2_follow_1
	buffer_wbl2 sc1
	s_waitcnt vmcnt(0)
	v_mov_b32_e32 v14, 0x2400
	v_mov_b32_e32 v15, 1
	global_atomic_add v14, v15, s[52:53]
	global_atomic_add v14, v15, s[52:53] offset:256
	global_atomic_add v14, v15, s[52:53] offset:512
	global_atomic_add v14, v15, s[52:53] offset:768
	global_atomic_add v14, v15, s[52:53] offset:1024
	global_atomic_add v14, v15, s[52:53] offset:1280
	global_atomic_add v14, v15, s[52:53] offset:1536
	global_atomic_add v14, v15, s[52:53] offset:1792
	global_atomic_add v14, v15, s[52:53] offset:2048
	global_atomic_add v14, v15, s[52:53] offset:2304
	global_atomic_add v14, v15, s[52:53] offset:2560
	global_atomic_add v14, v15, s[52:53] offset:2816
	global_atomic_add v14, v15, s[52:53] offset:3072
	global_atomic_add v14, v15, s[52:53] offset:3328
	global_atomic_add v14, v15, s[52:53] offset:3584
	global_atomic_add v14, v15, s[52:53] offset:3840
	s_mov_b64 vcc, exec
.Lxb2_follow_1:
	s_and_saveexec_b64 s[2:3], vcc
	s_xor_b64 s[6:7], exec, s[2:3]
	s_cbranch_execz .LBB0_203
	s_waitcnt lgkmcnt(0)
	v_mov_b32_e32 v0, 0x2000
	global_load_dword v0, v0, s[4:5] offset:1024 sc1
	s_add_u32 s10, s4, 0x2400
	s_addc_u32 s11, s5, 0
	s_waitcnt vmcnt(0)
	v_cmp_lt_u32_e32 vcc, v0, v1
	s_and_saveexec_b64 s[8:9], vcc
	s_cbranch_execz .LBB0_202
	s_mov_b32 s2, 1
	s_mov_b64 s[12:13], 0
	v_mov_b32_e32 v0, 0
	s_branch .LBB0_193

; __device__ __forceinline__ unsigned xb_ld(unsigned* p)              { return __hip_atomic_load(p, __ATOMIC_RELAXED, __HIP_MEMORY_SCOPE_AGENT); }
; #define XB_SPIN(cond, bar) do { unsigned _sp = 0; while (cond) { __builtin_amdgcn_s_sleep(1); \
;     if ((++_sp & 255u) == 0u) { if (xb_ld(&(bar)[XB_TMO])) break; if (_sp > XB_SPIN_CAP) { atomicAdd(&(bar)[XB_TMO], 1u); break; } } } } while (0)
; __device__ __forceinline__ void xcd_barrier(unsigned* bar, volatile LAS unsigned* st, bool tid0) {
;     ...
;             XB_SPIN(xb_ld(&bar[XB_XGEN(x)]) == gen, bar);
;             __builtin_amdgcn_fence(__ATOMIC_ACQUIRE, "agent");
;             asm volatile("s_waitcnt vmcnt(0)" ::: "memory");
.LBB0_195:
	global_load_dword v2, v0, s[10:11] sc1
	s_add_i32 s2, s2, 1
	s_mov_b64 s[18:19], -1
	s_waitcnt vmcnt(0)
	v_cmp_ge_u32_e32 vcc, v2, v1
	s_orn2_b64 s[16:17], vcc, exec
	s_branch .LBB0_192

; __device__ __forceinline__ unsigned xb_ld(unsigned* p)              { return __hip_atomic_load(p, __ATOMIC_RELAXED, __HIP_MEMORY_SCOPE_AGENT); }
; __device__ __forceinline__ unsigned xb_add(unsigned* p, unsigned v) { return __hip_atomic_fetch_add(p, v, __ATOMIC_RELAXED, __HIP_MEMORY_SCOPE_AGENT); }
; #define XB_SPIN(cond, bar) do { unsigned _sp = 0; while (cond) { __builtin_amdgcn_s_sleep(1); \
;     if ((++_sp & 255u) == 0u) { if (xb_ld(&(bar)[XB_TMO])) break; if (_sp > XB_SPIN_CAP) { atomicAdd(&(bar)[XB_TMO], 1u); break; } } } } while (0)
; __device__ __forceinline__ void xcd_barrier(unsigned* bar, volatile LAS unsigned* st, bool tid0) {
;     ...
;         __builtin_amdgcn_s_waitcnt(0);
;         unsigned nloc = st[0], nx = st[1];
;         if (nloc == 0u) { xcd_barrier_complete(bar, x, nloc, nx); st[0] = nloc; st[1] = nx; }
;         const unsigned old = xb_add(&bar[XB_XSUB(x)], 1u);
;         const unsigned gen = old / nloc;
;         if (old + 1u == (gen + 1u) * nloc) {
;             __builtin_amdgcn_fence(__ATOMIC_RELEASE, "agent");
;             asm volatile("s_waitcnt vmcnt(0)" ::: "memory");
;             const unsigned og = xb_add(&bar[XB_TOP], 1u);
;             const unsigned tg = og / nx;
;             if (og + 1u == (tg + 1u) * nx) xb_add(&bar[XB_TOPGEN], 1u);
;             else XB_SPIN(xb_ld(&bar[XB_TOPGEN]) == tg, bar);
;             __builtin_amdgcn_fence(__ATOMIC_ACQUIRE, "agent");
;             xb_add(&bar[XB_XGEN(x)], 1u);
;             asm volatile("s_waitcnt vmcnt(0)" ::: "memory");
;         } else {
;             XB_SPIN(xb_ld(&bar[XB_XGEN(x)]) == gen, bar);
;             __builtin_amdgcn_fence(__ATOMIC_ACQUIRE, "agent");
;             asm volatile("s_waitcnt vmcnt(0)" ::: "memory");
;         }
.LBB0_253:
	s_or_b64 exec, exec, s[8:9]
	buffer_inv sc1
	v_cvt_f32_u32_e32 v4, v2
	s_waitcnt vmcnt(1)
	v_readfirstlane_b32 s3, v3
	v_sub_u32_e32 v3, 0, v2
	v_rcp_iflag_f32_e32 v4, v4
	v_add_u32_e32 v5, s3, v1
	v_mul_f32_e32 v4, 0x4f7ffffe, v4
	v_cvt_u32_f32_e32 v4, v4
	v_mul_lo_u32 v1, v3, v4
	v_mul_hi_u32 v1, v4, v1
	v_add_u32_e32 v1, v4, v1
	v_mul_hi_u32 v1, v5, v1
	v_mul_lo_u32 v3, v1, v2
	v_sub_u32_e32 v3, v5, v3
	v_add_u32_e32 v4, 1, v1
	v_cmp_ge_u32_e32 vcc, v3, v2
	s_nop 1
	v_cndmask_b32_e32 v1, v1, v4, vcc
	v_sub_u32_e32 v4, v3, v2
	v_cndmask_b32_e32 v3, v3, v4, vcc
	v_add_u32_e32 v4, 1, v1
	v_cmp_ge_u32_e32 vcc, v3, v2
	v_add_u32_e32 v3, 1, v5
	s_nop 0
	v_cndmask_b32_e32 v1, v1, v4, vcc
	v_mul_lo_u32 v4, v2, v1
	v_add_u32_e32 v2, v4, v2
	v_cmp_ne_u32_e32 vcc, v3, v2
	s_waitcnt lgkmcnt(0)
	v_add_u32_e32 v1, 1, v1
	v_mul_lo_u32 v1, v1, v0
	s_cbranch_vccnz .Lxb2_follow_2
	buffer_wbl2 sc1
	s_waitcnt vmcnt(0)
	v_mov_b32_e32 v14, 0x2400
	v_mov_b32_e32 v15, 1
	global_atomic_add v14, v15, s[52:53]
	global_atomic_add v14, v15, s[52:53] offset:256
	global_atomic_add v14, v15, s[52:53] offset:512
	global_atomic_add v14, v15, s[52:53] offset:768
	global_atomic_add v14, v15, s[52:53] offset:1024
	global_atomic_add v14, v15, s[52:53] offset:1280
	global_atomic_add v14, v15, s[52:53] offset:1536
	global_atomic_add v14, v15, s[52:53] offset:1792
	global_atomic_add v14, v15, s[52:53] offset:2048
	global_atomic_add v14, v15, s[52:53] offset:2304
	global_atomic_add v14, v15, s[52:53] offset:2560
	global_atomic_add v14, v15, s[52:53] offset:2816
	global_atomic_add v14, v15, s[52:53] offset:3072
	global_atomic_add v14, v15, s[52:53] offset:3328
	global_atomic_add v14, v15, s[52:53] offset:3584
	global_atomic_add v14, v15, s[52:53] offset:3840
	s_mov_b64 vcc, exec
.Lxb2_follow_2:
	s_and_saveexec_b64 s[6:7], vcc
	s_xor_b64 s[6:7], exec, s[6:7]
	s_cbranch_execz .LBB0_267
	s_waitcnt lgkmcnt(0)
	v_mov_b32_e32 v0, 0x2000
	global_load_dword v0, v0, s[4:5] offset:1024 sc1
	s_add_u32 s10, s4, 0x2400
	s_addc_u32 s11, s5, 0
	s_waitcnt vmcnt(0)
	v_cmp_lt_u32_e32 vcc, v0, v1
	s_and_saveexec_b64 s[8:9], vcc
	s_cbranch_execz .LBB0_266
	s_mov_b32 s3, 1
	s_mov_b64 s[16:17], 0
	v_mov_b32_e32 v0, 0
	s_branch .LBB0_257

; __device__ __forceinline__ unsigned xb_ld(unsigned* p)              { return __hip_atomic_load(p, __ATOMIC_RELAXED, __HIP_MEMORY_SCOPE_AGENT); }
; #define XB_SPIN(cond, bar) do { unsigned _sp = 0; while (cond) { __builtin_amdgcn_s_sleep(1); \
;     if ((++_sp & 255u) == 0u) { if (xb_ld(&(bar)[XB_TMO])) break; if (_sp > XB_SPIN_CAP) { atomicAdd(&(bar)[XB_TMO], 1u); break; } } } } while (0)
; __device__ __forceinline__ void xcd_barrier(unsigned* bar, volatile LAS unsigned* st, bool tid0) {
;     ...
;             XB_SPIN(xb_ld(&bar[XB_XGEN(x)]) == gen, bar);
;             __builtin_amdgcn_fence(__ATOMIC_ACQUIRE, "agent");
;             asm volatile("s_waitcnt vmcnt(0)" ::: "memory");
.LBB0_259:
	global_load_dword v2, v0, s[10:11] sc1
	s_add_i32 s3, s3, 1
	s_mov_b64 s[22:23], -1
	s_waitcnt vmcnt(0)
	v_cmp_ge_u32_e32 vcc, v2, v1
	s_orn2_b64 s[20:21], vcc, exec
	s_branch .LBB0_256

; __device__ __forceinline__ unsigned xb_ld(unsigned* p)              { return __hip_atomic_load(p, __ATOMIC_RELAXED, __HIP_MEMORY_SCOPE_AGENT); }
; __device__ __forceinline__ unsigned xb_add(unsigned* p, unsigned v) { return __hip_atomic_fetch_add(p, v, __ATOMIC_RELAXED, __HIP_MEMORY_SCOPE_AGENT); }
; #define XB_SPIN(cond, bar) do { unsigned _sp = 0; while (cond) { __builtin_amdgcn_s_sleep(1); \
;     if ((++_sp & 255u) == 0u) { if (xb_ld(&(bar)[XB_TMO])) break; if (_sp > XB_SPIN_CAP) { atomicAdd(&(bar)[XB_TMO], 1u); break; } } } } while (0)
; __device__ __forceinline__ void xcd_barrier(unsigned* bar, volatile LAS unsigned* st, bool tid0) {
;     ...
;         __builtin_amdgcn_s_waitcnt(0);
;         unsigned nloc = st[0], nx = st[1];
;         if (nloc == 0u) { xcd_barrier_complete(bar, x, nloc, nx); st[0] = nloc; st[1] = nx; }
;         const unsigned old = xb_add(&bar[XB_XSUB(x)], 1u);
;         const unsigned gen = old / nloc;
;         if (old + 1u == (gen + 1u) * nloc) {
;             __builtin_amdgcn_fence(__ATOMIC_RELEASE, "agent");
;             asm volatile("s_waitcnt vmcnt(0)" ::: "memory");
;             const unsigned og = xb_add(&bar[XB_TOP], 1u);
;             const unsigned tg = og / nx;
;             if (og + 1u == (tg + 1u) * nx) xb_add(&bar[XB_TOPGEN], 1u);
;             else XB_SPIN(xb_ld(&bar[XB_TOPGEN]) == tg, bar);
;             __builtin_amdgcn_fence(__ATOMIC_ACQUIRE, "agent");
;             xb_add(&bar[XB_XGEN(x)], 1u);
;             asm volatile("s_waitcnt vmcnt(0)" ::: "memory");
;         } else {
;             XB_SPIN(xb_ld(&bar[XB_XGEN(x)]) == gen, bar);
;             __builtin_amdgcn_fence(__ATOMIC_ACQUIRE, "agent");
;             asm volatile("s_waitcnt vmcnt(0)" ::: "memory");
;         }
.LBB0_570:
	s_or_b64 exec, exec, s[12:13]
	buffer_inv sc1
	v_cvt_f32_u32_e32 v4, v2
	s_waitcnt vmcnt(1)
	v_readfirstlane_b32 s2, v3
	v_sub_u32_e32 v3, 0, v2
	v_rcp_iflag_f32_e32 v4, v4
	v_add_u32_e32 v5, s2, v1
	v_mul_f32_e32 v4, 0x4f7ffffe, v4
	v_cvt_u32_f32_e32 v4, v4
	v_mul_lo_u32 v1, v3, v4
	v_mul_hi_u32 v1, v4, v1
	v_add_u32_e32 v1, v4, v1
	v_mul_hi_u32 v1, v5, v1
	v_mul_lo_u32 v3, v1, v2
	v_sub_u32_e32 v3, v5, v3
	v_add_u32_e32 v4, 1, v1
	v_cmp_ge_u32_e32 vcc, v3, v2
	s_nop 1
	v_cndmask_b32_e32 v1, v1, v4, vcc
	v_sub_u32_e32 v4, v3, v2
	v_cndmask_b32_e32 v3, v3, v4, vcc
	v_add_u32_e32 v4, 1, v1
	v_cmp_ge_u32_e32 vcc, v3, v2
	v_add_u32_e32 v3, 1, v5
	s_nop 0
	v_cndmask_b32_e32 v1, v1, v4, vcc
	v_mul_lo_u32 v4, v2, v1
	v_add_u32_e32 v2, v4, v2
	v_cmp_ne_u32_e32 vcc, v3, v2
	s_waitcnt lgkmcnt(0)
	v_add_u32_e32 v1, 1, v1
	v_mul_lo_u32 v1, v1, v0
	s_cbranch_vccnz .Lxb2_follow_5
	buffer_wbl2 sc1
	s_waitcnt vmcnt(0)
	v_mov_b32_e32 v14, 0x2400
	v_mov_b32_e32 v15, 1
	global_atomic_add v14, v15, s[52:53]
	global_atomic_add v14, v15, s[52:53] offset:256
	global_atomic_add v14, v15, s[52:53] offset:512
	global_atomic_add v14, v15, s[52:53] offset:768
	global_atomic_add v14, v15, s[52:53] offset:1024
	global_atomic_add v14, v15, s[52:53] offset:1280
	global_atomic_add v14, v15, s[52:53] offset:1536
	global_atomic_add v14, v15, s[52:53] offset:1792
	global_atomic_add v14, v15, s[52:53] offset:2048
	global_atomic_add v14, v15, s[52:53] offset:2304
	global_atomic_add v14, v15, s[52:53] offset:2560
	global_atomic_add v14, v15, s[52:53] offset:2816
	global_atomic_add v14, v15, s[52:53] offset:3072
	global_atomic_add v14, v15, s[52:53] offset:3328
	global_atomic_add v14, v15, s[52:53] offset:3584
	global_atomic_add v14, v15, s[52:53] offset:3840
	s_mov_b64 vcc, exec
.Lxb2_follow_5:
	s_and_saveexec_b64 s[2:3], vcc
	s_xor_b64 s[10:11], exec, s[2:3]
	s_cbranch_execz .LBB0_584
	s_waitcnt lgkmcnt(0)
	v_mov_b32_e32 v0, 0x2000
	global_load_dword v0, v0, s[6:7] offset:1024 sc1
	s_add_u32 s14, s6, 0x2400
	s_addc_u32 s15, s7, 0
	s_waitcnt vmcnt(0)
	v_cmp_lt_u32_e32 vcc, v0, v1
	s_and_saveexec_b64 s[12:13], vcc
	s_cbranch_execz .LBB0_583
	s_mov_b32 s2, 1
	s_mov_b64 s[16:17], 0
	v_mov_b32_e32 v0, 0
	s_branch .LBB0_574

; __device__ __forceinline__ unsigned xb_ld(unsigned* p)              { return __hip_atomic_load(p, __ATOMIC_RELAXED, __HIP_MEMORY_SCOPE_AGENT); }
; #define XB_SPIN(cond, bar) do { unsigned _sp = 0; while (cond) { __builtin_amdgcn_s_sleep(1); \
;     if ((++_sp & 255u) == 0u) { if (xb_ld(&(bar)[XB_TMO])) break; if (_sp > XB_SPIN_CAP) { atomicAdd(&(bar)[XB_TMO], 1u); break; } } } } while (0)
; __device__ __forceinline__ void xcd_barrier(unsigned* bar, volatile LAS unsigned* st, bool tid0) {
;     ...
;             XB_SPIN(xb_ld(&bar[XB_XGEN(x)]) == gen, bar);
;             __builtin_amdgcn_fence(__ATOMIC_ACQUIRE, "agent");
;             asm volatile("s_waitcnt vmcnt(0)" ::: "memory");
.LBB0_576:
	global_load_dword v2, v0, s[14:15] sc1
	s_add_i32 s2, s2, 1
	s_mov_b64 s[22:23], -1
	s_waitcnt vmcnt(0)
	v_cmp_ge_u32_e32 vcc, v2, v1
	s_orn2_b64 s[20:21], vcc, exec
	s_branch .LBB0_573

; __device__ __forceinline__ unsigned xb_ld(unsigned* p)              { return __hip_atomic_load(p, __ATOMIC_RELAXED, __HIP_MEMORY_SCOPE_AGENT); }
; #define XB_SPIN(cond, bar) do { unsigned _sp = 0; while (cond) { __builtin_amdgcn_s_sleep(1); \
;     if ((++_sp & 255u) == 0u) { if (xb_ld(&(bar)[XB_TMO])) break; if (_sp > XB_SPIN_CAP) { atomicAdd(&(bar)[XB_TMO], 1u); break; } } } } while (0)
; __device__ __forceinline__ void xcd_barrier(unsigned* bar, volatile LAS unsigned* st, bool tid0) {
;     ...
;             XB_SPIN(xb_ld(&bar[XB_XGEN(x)]) == gen, bar);
;             __builtin_amdgcn_fence(__ATOMIC_ACQUIRE, "agent");
;             asm volatile("s_waitcnt vmcnt(0)" ::: "memory");
.Lxb2_follow_6:
	s_and_saveexec_b64 s[2:3], vcc
	s_xor_b64 s[8:9], exec, s[2:3]
	s_cbranch_execz .LBB0_675
	s_waitcnt lgkmcnt(0)
	v_mov_b32_e32 v0, 0x2000
	global_load_dword v0, v0, s[6:7] offset:1024 sc1
	s_add_u32 s14, s6, 0x2400
	s_addc_u32 s15, s7, 0
	s_waitcnt vmcnt(0)
	v_cmp_lt_u32_e32 vcc, v0, v1
	s_and_saveexec_b64 s[12:13], vcc
	s_cbranch_execz .LBB0_674
	s_mov_b32 s2, 1
	s_mov_b64 s[16:17], 0
	v_mov_b32_e32 v0, 0
	s_branch .LBB0_665

; __device__ __forceinline__ unsigned xb_ld(unsigned* p)              { return __hip_atomic_load(p, __ATOMIC_RELAXED, __HIP_MEMORY_SCOPE_AGENT); }
; __device__ __forceinline__ unsigned xb_add(unsigned* p, unsigned v) { return __hip_atomic_fetch_add(p, v, __ATOMIC_RELAXED, __HIP_MEMORY_SCOPE_AGENT); }
; #define XB_SPIN(cond, bar) do { unsigned _sp = 0; while (cond) { __builtin_amdgcn_s_sleep(1); \
;     if ((++_sp & 255u) == 0u) { if (xb_ld(&(bar)[XB_TMO])) break; if (_sp > XB_SPIN_CAP) { atomicAdd(&(bar)[XB_TMO], 1u); break; } } } } while (0)
; __device__ __forceinline__ void xcd_barrier(unsigned* bar, volatile LAS unsigned* st, bool tid0) {
;     ...
;         __builtin_amdgcn_s_waitcnt(0);
;         unsigned nloc = st[0], nx = st[1];
;         if (nloc == 0u) { xcd_barrier_complete(bar, x, nloc, nx); st[0] = nloc; st[1] = nx; }
;         const unsigned old = xb_add(&bar[XB_XSUB(x)], 1u);
;         const unsigned gen = old / nloc;
;         if (old + 1u == (gen + 1u) * nloc) {
;             __builtin_amdgcn_fence(__ATOMIC_RELEASE, "agent");
;             asm volatile("s_waitcnt vmcnt(0)" ::: "memory");
;             const unsigned og = xb_add(&bar[XB_TOP], 1u);
;             const unsigned tg = og / nx;
;             if (og + 1u == (tg + 1u) * nx) xb_add(&bar[XB_TOPGEN], 1u);
;             else XB_SPIN(xb_ld(&bar[XB_TOPGEN]) == tg, bar);
;             __builtin_amdgcn_fence(__ATOMIC_ACQUIRE, "agent");
;             xb_add(&bar[XB_XGEN(x)], 1u);
;             asm volatile("s_waitcnt vmcnt(0)" ::: "memory");
;         } else {
;             XB_SPIN(xb_ld(&bar[XB_XGEN(x)]) == gen, bar);
;             __builtin_amdgcn_fence(__ATOMIC_ACQUIRE, "agent");
;             asm volatile("s_waitcnt vmcnt(0)" ::: "memory");
;         }
.LBB0_788:
	s_or_b64 exec, exec, s[14:15]
	buffer_inv sc1
	v_cvt_f32_u32_e32 v4, v2
	s_waitcnt vmcnt(1)
	v_readfirstlane_b32 s2, v3
	v_sub_u32_e32 v3, 0, v2
	v_rcp_iflag_f32_e32 v4, v4
	v_add_u32_e32 v5, s2, v1
	v_mul_f32_e32 v4, 0x4f7ffffe, v4
	v_cvt_u32_f32_e32 v4, v4
	v_mul_lo_u32 v1, v3, v4
	v_mul_hi_u32 v1, v4, v1
	v_add_u32_e32 v1, v4, v1
	v_mul_hi_u32 v1, v5, v1
	v_mul_lo_u32 v3, v1, v2
	v_sub_u32_e32 v3, v5, v3
	v_add_u32_e32 v4, 1, v1
	v_cmp_ge_u32_e32 vcc, v3, v2
	s_nop 1
	v_cndmask_b32_e32 v1, v1, v4, vcc
	v_sub_u32_e32 v4, v3, v2
	v_cndmask_b32_e32 v3, v3, v4, vcc
	v_add_u32_e32 v4, 1, v1
	v_cmp_ge_u32_e32 vcc, v3, v2
	v_add_u32_e32 v3, 1, v5
	s_nop 0
	v_cndmask_b32_e32 v1, v1, v4, vcc
	v_mul_lo_u32 v4, v2, v1
	v_add_u32_e32 v2, v4, v2
	v_cmp_ne_u32_e32 vcc, v3, v2
	s_waitcnt lgkmcnt(0)
	v_add_u32_e32 v1, 1, v1
	v_mul_lo_u32 v1, v1, v0
	s_cbranch_vccnz .Lxb2_follow_8
	buffer_wbl2 sc1
	s_waitcnt vmcnt(0)
	v_mov_b32_e32 v14, 0x2400
	v_mov_b32_e32 v15, 1
	global_atomic_add v14, v15, s[52:53]
	global_atomic_add v14, v15, s[52:53] offset:256
	global_atomic_add v14, v15, s[52:53] offset:512
	global_atomic_add v14, v15, s[52:53] offset:768
	global_atomic_add v14, v15, s[52:53] offset:1024
	global_atomic_add v14, v15, s[52:53] offset:1280
	global_atomic_add v14, v15, s[52:53] offset:1536
	global_atomic_add v14, v15, s[52:53] offset:1792
	global_atomic_add v14, v15, s[52:53] offset:2048
	global_atomic_add v14, v15, s[52:53] offset:2304
	global_atomic_add v14, v15, s[52:53] offset:2560
	global_atomic_add v14, v15, s[52:53] offset:2816
	global_atomic_add v14, v15, s[52:53] offset:3072
	global_atomic_add v14, v15, s[52:53] offset:3328
	global_atomic_add v14, v15, s[52:53] offset:3584
	global_atomic_add v14, v15, s[52:53] offset:3840
	s_mov_b64 vcc, exec
.Lxb2_follow_8:
	s_and_saveexec_b64 s[2:3], vcc
	s_xor_b64 s[8:9], exec, s[2:3]
	s_cbranch_execz .LBB0_802
	s_waitcnt lgkmcnt(0)
	v_mov_b32_e32 v0, 0x2000
	global_load_dword v0, v0, s[6:7] offset:1024 sc1
	s_add_u32 s16, s6, 0x2400
	s_addc_u32 s17, s7, 0
	s_waitcnt vmcnt(0)
	v_cmp_lt_u32_e32 vcc, v0, v1
	s_and_saveexec_b64 s[14:15], vcc
	s_cbranch_execz .LBB0_801
	s_mov_b32 s2, 1
	s_mov_b64 s[18:19], 0
	v_mov_b32_e32 v0, 0
	s_branch .LBB0_792

; __device__ __forceinline__ unsigned xb_ld(unsigned* p)              { return __hip_atomic_load(p, __ATOMIC_RELAXED, __HIP_MEMORY_SCOPE_AGENT); }
; #define XB_SPIN(cond, bar) do { unsigned _sp = 0; while (cond) { __builtin_amdgcn_s_sleep(1); \
;     if ((++_sp & 255u) == 0u) { if (xb_ld(&(bar)[XB_TMO])) break; if (_sp > XB_SPIN_CAP) { atomicAdd(&(bar)[XB_TMO], 1u); break; } } } } while (0)
; __device__ __forceinline__ void xcd_barrier(unsigned* bar, volatile LAS unsigned* st, bool tid0) {
;     ...
;             XB_SPIN(xb_ld(&bar[XB_XGEN(x)]) == gen, bar);
;             __builtin_amdgcn_fence(__ATOMIC_ACQUIRE, "agent");
;             asm volatile("s_waitcnt vmcnt(0)" ::: "memory");
.LBB0_794:
	global_load_dword v2, v0, s[16:17] sc1
	s_add_i32 s2, s2, 1
	s_mov_b64 s[24:25], -1
	s_waitcnt vmcnt(0)
	v_cmp_ge_u32_e32 vcc, v2, v1
	s_orn2_b64 s[22:23], vcc, exec
	s_branch .LBB0_791

; __device__ __forceinline__ unsigned xb_ld(unsigned* p)              { return __hip_atomic_load(p, __ATOMIC_RELAXED, __HIP_MEMORY_SCOPE_AGENT); }
; __device__ __forceinline__ unsigned xb_add(unsigned* p, unsigned v) { return __hip_atomic_fetch_add(p, v, __ATOMIC_RELAXED, __HIP_MEMORY_SCOPE_AGENT); }
; #define XB_SPIN(cond, bar) do { unsigned _sp = 0; while (cond) { __builtin_amdgcn_s_sleep(1); \
;     if ((++_sp & 255u) == 0u) { if (xb_ld(&(bar)[XB_TMO])) break; if (_sp > XB_SPIN_CAP) { atomicAdd(&(bar)[XB_TMO], 1u); break; } } } } while (0)
; __device__ __forceinline__ void xcd_barrier(unsigned* bar, volatile LAS unsigned* st, bool tid0) {
;     ...
;         __builtin_amdgcn_s_waitcnt(0);
;         unsigned nloc = st[0], nx = st[1];
;         if (nloc == 0u) { xcd_barrier_complete(bar, x, nloc, nx); st[0] = nloc; st[1] = nx; }
;         const unsigned old = xb_add(&bar[XB_XSUB(x)], 1u);
;         const unsigned gen = old / nloc;
;         if (old + 1u == (gen + 1u) * nloc) {
;             __builtin_amdgcn_fence(__ATOMIC_RELEASE, "agent");
;             asm volatile("s_waitcnt vmcnt(0)" ::: "memory");
;             const unsigned og = xb_add(&bar[XB_TOP], 1u);
;             const unsigned tg = og / nx;
;             if (og + 1u == (tg + 1u) * nx) xb_add(&bar[XB_TOPGEN], 1u);
;             else XB_SPIN(xb_ld(&bar[XB_TOPGEN]) == tg, bar);
;             __builtin_amdgcn_fence(__ATOMIC_ACQUIRE, "agent");
;             xb_add(&bar[XB_XGEN(x)], 1u);
;             asm volatile("s_waitcnt vmcnt(0)" ::: "memory");
;         } else {
;             XB_SPIN(xb_ld(&bar[XB_XGEN(x)]) == gen, bar);
;             __builtin_amdgcn_fence(__ATOMIC_ACQUIRE, "agent");
;             asm volatile("s_waitcnt vmcnt(0)" ::: "memory");
;         }
.LBB0_1050:
	s_or_b64 exec, exec, s[6:7]
	buffer_inv sc1
	v_cvt_f32_u32_e32 v4, v2
	s_waitcnt vmcnt(1)
	v_readfirstlane_b32 s4, v3
	v_sub_u32_e32 v3, 0, v2
	v_rcp_iflag_f32_e32 v4, v4
	v_add_u32_e32 v5, s4, v1
	v_mul_f32_e32 v4, 0x4f7ffffe, v4
	v_cvt_u32_f32_e32 v4, v4
	v_mul_lo_u32 v1, v3, v4
	v_mul_hi_u32 v1, v4, v1
	v_add_u32_e32 v1, v4, v1
	v_mul_hi_u32 v1, v5, v1
	v_mul_lo_u32 v3, v1, v2
	v_sub_u32_e32 v3, v5, v3
	v_add_u32_e32 v4, 1, v1
	v_cmp_ge_u32_e32 vcc, v3, v2
	s_nop 1
	v_cndmask_b32_e32 v1, v1, v4, vcc
	v_sub_u32_e32 v4, v3, v2
	v_cndmask_b32_e32 v3, v3, v4, vcc
	v_add_u32_e32 v4, 1, v1
	v_cmp_ge_u32_e32 vcc, v3, v2
	v_add_u32_e32 v3, 1, v5
	s_nop 0
	v_cndmask_b32_e32 v1, v1, v4, vcc
	v_mul_lo_u32 v4, v2, v1
	v_add_u32_e32 v2, v4, v2
	v_cmp_ne_u32_e32 vcc, v3, v2
	s_waitcnt lgkmcnt(0)
	v_add_u32_e32 v1, 1, v1
	v_mul_lo_u32 v1, v1, v0
	s_cbranch_vccnz .Lxb2_follow_11
	buffer_wbl2 sc1
	s_waitcnt vmcnt(0)
	v_mov_b32_e32 v14, 0x2400
	v_mov_b32_e32 v15, 1
	global_atomic_add v14, v15, s[52:53]
	global_atomic_add v14, v15, s[52:53] offset:256
	global_atomic_add v14, v15, s[52:53] offset:512
	global_atomic_add v14, v15, s[52:53] offset:768
	global_atomic_add v14, v15, s[52:53] offset:1024
	global_atomic_add v14, v15, s[52:53] offset:1280
	global_atomic_add v14, v15, s[52:53] offset:1536
	global_atomic_add v14, v15, s[52:53] offset:1792
	global_atomic_add v14, v15, s[52:53] offset:2048
	global_atomic_add v14, v15, s[52:53] offset:2304
	global_atomic_add v14, v15, s[52:53] offset:2560
	global_atomic_add v14, v15, s[52:53] offset:2816
	global_atomic_add v14, v15, s[52:53] offset:3072
	global_atomic_add v14, v15, s[52:53] offset:3328
	global_atomic_add v14, v15, s[52:53] offset:3584
	global_atomic_add v14, v15, s[52:53] offset:3840
	s_mov_b64 vcc, exec
.Lxb2_follow_11:
	s_and_saveexec_b64 s[4:5], vcc
	s_xor_b64 s[4:5], exec, s[4:5]
	s_cbranch_execz .LBB0_1064
	s_waitcnt lgkmcnt(0)
	v_mov_b32_e32 v0, 0x2000
	global_load_dword v0, v0, s[2:3] offset:1024 sc1
	s_add_u32 s8, s2, 0x2400
	s_addc_u32 s9, s3, 0
	s_waitcnt vmcnt(0)
	v_cmp_lt_u32_e32 vcc, v0, v1
	s_and_saveexec_b64 s[6:7], vcc
	s_cbranch_execz .LBB0_1063
	s_mov_b32 s22, 1
	s_mov_b64 s[12:13], 0
	v_mov_b32_e32 v0, 0
	s_branch .LBB0_1054

; __device__ __forceinline__ unsigned xb_ld(unsigned* p)              { return __hip_atomic_load(p, __ATOMIC_RELAXED, __HIP_MEMORY_SCOPE_AGENT); }
; #define XB_SPIN(cond, bar) do { unsigned _sp = 0; while (cond) { __builtin_amdgcn_s_sleep(1); \
;     if ((++_sp & 255u) == 0u) { if (xb_ld(&(bar)[XB_TMO])) break; if (_sp > XB_SPIN_CAP) { atomicAdd(&(bar)[XB_TMO], 1u); break; } } } } while (0)
; __device__ __forceinline__ void xcd_barrier(unsigned* bar, volatile LAS unsigned* st, bool tid0) {
;     ...
;             XB_SPIN(xb_ld(&bar[XB_XGEN(x)]) == gen, bar);
;             __builtin_amdgcn_fence(__ATOMIC_ACQUIRE, "agent");
;             asm volatile("s_waitcnt vmcnt(0)" ::: "memory");
.LBB0_1056:
	global_load_dword v2, v0, s[8:9] sc1
	s_add_i32 s22, s22, 1
	s_mov_b64 s[18:19], -1
	s_waitcnt vmcnt(0)
	v_cmp_ge_u32_e32 vcc, v2, v1
	s_orn2_b64 s[16:17], vcc, exec
	s_branch .LBB0_1053
